# attention output stores widened to dwordx4 via v_permlane32_swap (NSA and MoBA unit tails)
# speedup vs baseline: 1.0078x; 1.0078x over previous
.LBB0_61:
	v_mov_b32_e32 v0, v149
	s_nop 1
	v_permlane32_swap_b32_e32 v149, v0
	v_add_f32_e32 v0, v149, v0
	v_cmp_lt_f32_e32 vcc, 0, v0
	v_rcp_f32_e32 v0, v0
	ds_read2st64_b32 v[18:19], v132 offset1:1
	ds_read2st64_b32 v[20:21], v132 offset0:16 offset1:17
	s_lshl_b32 s6, s13, 7
	v_mul_f32_e32 v0, v192, v0
	v_cndmask_b32_e32 v0, 0, v0, vcc
	s_waitcnt lgkmcnt(0)
	v_pk_fma_f32 v[2:3], v[2:3], v[0:1], v[20:21] op_sel_hi:[1,0,1]
	ds_read2st64_b32 v[20:21], v132 offset0:2 offset1:3
	ds_read2st64_b32 v[22:23], v132 offset0:18 offset1:19
	v_pk_fma_f32 v[18:19], v[34:35], v[0:1], v[18:19] op_sel_hi:[1,0,1]
	v_cvt_pk_bf16_f32 v2, v2, v3
	v_cvt_pk_bf16_f32 v18, v18, v19
	s_waitcnt lgkmcnt(1)
	v_pk_fma_f32 v[20:21], v[36:37], v[0:1], v[20:21] op_sel_hi:[1,0,1]
	s_waitcnt lgkmcnt(0)
	v_pk_fma_f32 v[4:5], v[4:5], v[0:1], v[22:23] op_sel_hi:[1,0,1]
	ds_read2st64_b32 v[22:23], v132 offset0:4 offset1:5
	ds_read2st64_b32 v[24:25], v132 offset0:20 offset1:21
	v_cvt_pk_bf16_f32 v3, v4, v5
	v_cvt_pk_bf16_f32 v19, v20, v21
	s_waitcnt lgkmcnt(1)
	v_pk_fma_f32 v[22:23], v[38:39], v[0:1], v[22:23] op_sel_hi:[1,0,1]
	s_waitcnt lgkmcnt(0)
	v_pk_fma_f32 v[6:7], v[6:7], v[0:1], v[24:25] op_sel_hi:[1,0,1]
	ds_read2st64_b32 v[24:25], v132 offset0:6 offset1:7
	ds_read2st64_b32 v[26:27], v132 offset0:22 offset1:23
	s_waitcnt lgkmcnt(1)
	v_pk_fma_f32 v[24:25], v[40:41], v[0:1], v[24:25] op_sel_hi:[1,0,1]
	s_waitcnt lgkmcnt(0)
	v_pk_fma_f32 v[8:9], v[8:9], v[0:1], v[26:27] op_sel_hi:[1,0,1]
	ds_read2st64_b32 v[26:27], v132 offset0:8 offset1:9
	ds_read2st64_b32 v[28:29], v132 offset0:24 offset1:25
	s_waitcnt lgkmcnt(1)
	v_pk_fma_f32 v[26:27], v[42:43], v[0:1], v[26:27] op_sel_hi:[1,0,1]
	s_waitcnt lgkmcnt(0)
	v_pk_fma_f32 v[10:11], v[10:11], v[0:1], v[28:29] op_sel_hi:[1,0,1]
	ds_read2st64_b32 v[28:29], v132 offset0:10 offset1:11
	ds_read2st64_b32 v[30:31], v132 offset0:26 offset1:27
	s_waitcnt lgkmcnt(1)
	v_pk_fma_f32 v[28:29], v[44:45], v[0:1], v[28:29] op_sel_hi:[1,0,1]
	s_waitcnt lgkmcnt(0)
	v_pk_fma_f32 v[12:13], v[12:13], v[0:1], v[30:31] op_sel_hi:[1,0,1]
	ds_read2st64_b32 v[30:31], v132 offset0:12 offset1:13
	ds_read2st64_b32 v[32:33], v132 offset0:28 offset1:29
	s_waitcnt lgkmcnt(1)
	v_pk_fma_f32 v[30:31], v[46:47], v[0:1], v[30:31] op_sel_hi:[1,0,1]
	s_waitcnt lgkmcnt(0)
	v_pk_fma_f32 v[14:15], v[14:15], v[0:1], v[32:33] op_sel_hi:[1,0,1]
	ds_read2st64_b32 v[32:33], v132 offset0:14 offset1:15
	ds_read2st64_b32 v[34:35], v132 offset0:30 offset1:31
	s_waitcnt lgkmcnt(1)
	v_pk_fma_f32 v[32:33], v[48:49], v[0:1], v[32:33] op_sel_hi:[1,0,1]
	s_waitcnt lgkmcnt(0)
	v_pk_fma_f32 v[16:17], v[16:17], v[0:1], v[34:35] op_sel_hi:[1,0,1]
	v_lshlrev_b64 v[34:35], 11, v[94:95]
	v_lshl_add_u64 v[34:35], s[10:11], 0, v[34:35]
	v_lshl_add_u64 v[34:35], v[34:35], 0, s[6:7]
	v_lshlrev_b32_e32 v0, 1, v162
	v_lshl_add_u64 v[34:35], v[34:35], 0, v[0:1]
	v_lshlrev_b32_e32 v0, 3, v213
	v_lshl_add_u64 v[34:35], v[34:35], 0, v[0:1]
	v_mov_b32_e32 v36, v18
	v_mov_b32_e32 v37, v19
	v_cvt_pk_bf16_f32 v38, v22, v23
	v_cvt_pk_bf16_f32 v39, v24, v25
	v_cvt_pk_bf16_f32 v40, v26, v27
	v_cvt_pk_bf16_f32 v41, v28, v29
	v_cvt_pk_bf16_f32 v42, v30, v31
	v_cvt_pk_bf16_f32 v43, v32, v33
	v_mov_b32_e32 v44, v2
	v_mov_b32_e32 v45, v3
	v_cvt_pk_bf16_f32 v46, v6, v7
	v_cvt_pk_bf16_f32 v47, v8, v9
	v_cvt_pk_bf16_f32 v48, v10, v11
	v_cvt_pk_bf16_f32 v49, v12, v13
	v_cvt_pk_bf16_f32 v50, v14, v15
	v_cvt_pk_bf16_f32 v51, v16, v17
	s_nop 1
	v_permlane32_swap_b32_e32 v36, v38
	v_permlane32_swap_b32_e32 v37, v39
	v_permlane32_swap_b32_e32 v40, v42
	v_permlane32_swap_b32_e32 v41, v43
	v_permlane32_swap_b32_e32 v44, v46
	v_permlane32_swap_b32_e32 v45, v47
	v_permlane32_swap_b32_e32 v48, v50
	v_permlane32_swap_b32_e32 v49, v51
	global_store_dwordx4 v[34:35], v[36:39], off
	global_store_dwordx4 v[34:35], v[40:43], off offset:32
	global_store_dwordx4 v[34:35], v[44:47], off offset:64
	global_store_dwordx4 v[34:35], v[48:51], off offset:96
	s_setprio 0
	s_mov_b64 s[30:31], 0
	s_and_b64 vcc, exec, s[4:5]
	s_barrier
	s_cbranch_vccnz .LBB0_57

.LBB0_199:
	v_mov_b32_e32 v2, v0
	s_nop 1
	v_permlane32_swap_b32_e32 v0, v2
	v_add_f32_e32 v0, v0, v2
	v_rcp_f32_e32 v2, v0
	v_cmp_lt_f32_e32 vcc, 0, v0
	s_nop 1
	v_cndmask_b32_e32 v0, 0, v2, vcc
	v_pk_fma_f32 v[6:7], v[34:35], v[0:1], 0 op_sel_hi:[1,0,0]
	v_lshlrev_b64 v[34:35], 11, v[126:127]
	v_pk_fma_f32 v[2:3], v[32:33], v[0:1], 0 op_sel_hi:[1,0,0]
	v_pk_fma_f32 v[4:5], v[16:17], v[0:1], 0 op_sel_hi:[1,0,0]
	v_pk_fma_f32 v[8:9], v[18:19], v[0:1], 0 op_sel_hi:[1,0,0]
	v_pk_fma_f32 v[10:11], v[36:37], v[0:1], 0 op_sel_hi:[1,0,0]
	v_pk_fma_f32 v[12:13], v[20:21], v[0:1], 0 op_sel_hi:[1,0,0]
	v_pk_fma_f32 v[14:15], v[38:39], v[0:1], 0 op_sel_hi:[1,0,0]
	v_pk_fma_f32 v[16:17], v[22:23], v[0:1], 0 op_sel_hi:[1,0,0]
	v_pk_fma_f32 v[18:19], v[40:41], v[0:1], 0 op_sel_hi:[1,0,0]
	v_pk_fma_f32 v[20:21], v[24:25], v[0:1], 0 op_sel_hi:[1,0,0]
	v_pk_fma_f32 v[22:23], v[42:43], v[0:1], 0 op_sel_hi:[1,0,0]
	v_pk_fma_f32 v[24:25], v[26:27], v[0:1], 0 op_sel_hi:[1,0,0]
	v_pk_fma_f32 v[26:27], v[44:45], v[0:1], 0 op_sel_hi:[1,0,0]
	v_pk_fma_f32 v[28:29], v[28:29], v[0:1], 0 op_sel_hi:[1,0,0]
	v_pk_fma_f32 v[32:33], v[46:47], v[0:1], 0 op_sel_hi:[1,0,0]
	v_pk_fma_f32 v[30:31], v[30:31], v[0:1], 0 op_sel_hi:[1,0,0]
	v_lshl_add_u64 v[34:35], s[22:23], 0, v[34:35]
	v_lshlrev_b32_e32 v0, 1, v130
	v_lshl_add_u64 v[34:35], v[34:35], 0, v[0:1]
	v_mbcnt_lo_u32_b32 v56, -1, 0
	v_mbcnt_hi_u32_b32 v56, -1, v56
	v_and_b32_e32 v56, 32, v56
	v_lshrrev_b32_e32 v56, 2, v56
	v_mov_b32_e32 v57, 0
	v_lshl_add_u64 v[34:35], v[34:35], 0, v[56:57]
	v_cvt_pk_bf16_f32 v48, v2, v3
	v_cvt_pk_bf16_f32 v49, v6, v7
	v_cvt_pk_bf16_f32 v50, v10, v11
	v_cvt_pk_bf16_f32 v51, v14, v15
	v_cvt_pk_bf16_f32 v52, v18, v19
	v_cvt_pk_bf16_f32 v53, v22, v23
	v_cvt_pk_bf16_f32 v54, v26, v27
	v_cvt_pk_bf16_f32 v55, v32, v33
	v_cvt_pk_bf16_f32 v60, v4, v5
	v_cvt_pk_bf16_f32 v61, v8, v9
	v_cvt_pk_bf16_f32 v62, v12, v13
	v_cvt_pk_bf16_f32 v63, v16, v17
	v_cvt_pk_bf16_f32 v64, v20, v21
	v_cvt_pk_bf16_f32 v65, v24, v25
	v_cvt_pk_bf16_f32 v66, v28, v29
	v_cvt_pk_bf16_f32 v67, v30, v31
	s_nop 1
	v_permlane32_swap_b32_e32 v48, v50
	v_permlane32_swap_b32_e32 v49, v51
	v_permlane32_swap_b32_e32 v52, v54
	v_permlane32_swap_b32_e32 v53, v55
	v_permlane32_swap_b32_e32 v60, v62
	v_permlane32_swap_b32_e32 v61, v63
	v_permlane32_swap_b32_e32 v64, v66
	v_permlane32_swap_b32_e32 v65, v67
	global_store_dwordx4 v[34:35], v[48:51], off offset:1024
	global_store_dwordx4 v[34:35], v[52:55], off offset:1056
	global_store_dwordx4 v[34:35], v[60:63], off offset:1088
	global_store_dwordx4 v[34:35], v[64:67], off offset:1120
	s_setprio 0
	s_add_i32 s3, s3, 1
	s_cmp_gt_u32 s9, s3
	s_cselect_b64 s[0:1], -1, 0
	s_and_b64 s[0:1], s[20:21], s[0:1]
	s_andn2_b64 vcc, exec, s[0:1]
	s_barrier
	s_cbranch_vccnz .LBB0_154
